# MLA fast path unrolled by tile parity: even copy carries the DMA block, odd copy the pair barrier, no parity flags or parity branches; even-to-odd transition falls through
# speedup vs baseline: 1.0068x; 1.0068x over previous
.Lmla_fast:
	s_and_b32 s8, s30, 3
	s_mulk_i32 s8, 0x6400
	s_add_i32 s8, s8, 0
	v_add3_u32 v142, s8, v144, v145
	v_add3_u32 v0, s8, v143, v132
	ds_read_b128 v[194:197], v0
	ds_read_b128 v[150:153], v0 offset:32
	ds_read_b128 v[158:161], v0 offset:64
	ds_read_b128 v[162:165], v0 offset:96
	ds_read_b128 v[174:177], v0 offset:128
	ds_read_b128 v[178:181], v0 offset:160
	s_bitcmp1_b32 s30, 0
	s_cbranch_scc1 .Lmla_fast_havek_o
.Lmla_fast_havek_e:
	s_mov_b32 s42, 0
	s_add_i32 s34, s30, 2
	s_cmp_gt_u32 s34, s14
	s_cbranch_scc1 .Lmla_fast_d2_e
	s_and_b32 s8, s34, 2
	s_mulk_i32 s8, 0x6400
	s_add_i32 s34, s8, 0
	s_add_i32 s8, s34, s5
	s_mov_b32 m0, s8
	s_and_b64 vcc, exec, s[36:37]
	global_load_lds_dwordx4 v66, s[26:27]
	s_add_i32 m0, s8, 0x2000
	v_add_u32_e32 v66, v66, v134
	global_load_lds_dwordx4 v68, s[26:27]
	s_add_i32 m0, s8, 0x4000
	v_add_u32_e32 v68, v68, v136
	global_load_lds_dwordx4 v70, s[26:27]
	v_add_u32_e32 v70, v70, v138
	s_cbranch_vccnz .Lmla_fast_d2_e
	s_add_i32 m0, s34, 0x6000
	s_nop 0
	global_load_lds_dwordx4 v72, s[26:27]
	v_add_u32_e32 v72, v72, v140

.Lmla_fast_nodma_e:
	s_waitcnt lgkmcnt(0)
	v_mfma_f32_32x32x16_bf16 v[50:65], v[194:197], v[74:77], v[234:249]
	ds_read_b128 v[194:197], v0 offset:6656
	v_add_f32_e32 v254, v202, v203
	v_add_f32_e32 v255, v204, v205
	v_add_f32_e32 v254, v254, v206
	v_add_f32_e32 v255, v255, v207
	v_add_f32_e32 v254, v254, v208
	v_add_f32_e32 v255, v255, v209
	v_mfma_f32_32x32x16_bf16 v[50:65], v[150:153], v[78:81], v[50:65]
	ds_read_b128 v[150:153], v0 offset:6688
	v_add_f32_e32 v254, v254, v210
	v_add_f32_e32 v255, v255, v211
	v_add_f32_e32 v254, v254, v212
	v_add_f32_e32 v255, v255, v213
	v_add_f32_e32 v254, v254, v214
	v_add_f32_e32 v255, v255, v215
	v_mfma_f32_32x32x16_bf16 v[50:65], v[158:161], v[82:85], v[50:65]
	ds_read_b128 v[158:161], v0 offset:6720
	v_add_f32_e32 v254, v254, v216
	v_add_f32_e32 v255, v255, v217
	v_add_f32_e32 v254, v254, v218
	v_add_f32_e32 v255, v255, v219
	v_add_f32_e32 v254, v254, v220
	v_mfma_f32_32x32x16_bf16 v[50:65], v[162:165], v[86:89], v[50:65]
	ds_read_b128 v[162:165], v0 offset:6752
	v_add_f32_e32 v255, v255, v221
	v_add_f32_e32 v254, v254, v222
	v_add_f32_e32 v255, v255, v223
	v_add_f32_e32 v254, v254, v224
	v_add_f32_e32 v255, v255, v225
	v_mfma_f32_32x32x16_bf16 v[50:65], v[174:177], v[90:93], v[50:65]
	ds_read_b128 v[174:177], v0 offset:6784
	v_add_f32_e32 v254, v254, v226
	v_add_f32_e32 v255, v255, v227
	v_add_f32_e32 v254, v254, v228
	v_add_f32_e32 v255, v255, v229
	v_add_f32_e32 v254, v254, v230
	v_mfma_f32_32x32x16_bf16 v[50:65], v[178:181], v[94:97], v[50:65]
	ds_read_b128 v[178:181], v0 offset:6816
	v_add_f32_e32 v255, v255, v231
	v_add_f32_e32 v254, v254, v232
	v_add_f32_e32 v255, v255, v233
	v_add_f32_e32 v254, v254, v255
	v_add_f32_e32 v147, v147, v254
	s_waitcnt lgkmcnt(5)
	v_mfma_f32_32x32x16_bf16 v[34:49], v[194:197], v[74:77], v[234:249]
	ds_read_b64_tr_b16 v[126:127], v142 offset:13312
	ds_read_b64_tr_b16 v[128:129], v142 offset:14848
	ds_read_b64_tr_b16 v[124:125], v142 offset:14912
	ds_read_b64_tr_b16 v[122:123], v142 offset:13376
	s_waitcnt lgkmcnt(8)
	v_mfma_f32_32x32x16_bf16 v[34:49], v[150:153], v[78:81], v[34:49]
	ds_read_b64_tr_b16 v[118:119], v142 offset:16384
	ds_read_b64_tr_b16 v[120:121], v142 offset:17920
	ds_read_b64_tr_b16 v[116:117], v142 offset:17984
	ds_read_b64_tr_b16 v[114:115], v142 offset:16448
	s_waitcnt lgkmcnt(11)
	v_mfma_f32_32x32x16_bf16 v[34:49], v[158:161], v[82:85], v[34:49]
	ds_read_b64_tr_b16 v[110:111], v142 offset:19456
	ds_read_b64_tr_b16 v[112:113], v142 offset:20992
	ds_read_b64_tr_b16 v[108:109], v142 offset:21056
	ds_read_b64_tr_b16 v[106:107], v142 offset:19520
	s_waitcnt lgkmcnt(11)
	v_mfma_f32_32x32x16_bf16 v[34:49], v[162:165], v[86:89], v[34:49]
	ds_read_b64_tr_b16 v[102:103], v142 offset:22528
	ds_read_b64_tr_b16 v[104:105], v142 offset:24064
	ds_read_b64_tr_b16 v[100:101], v142 offset:24128
	ds_read_b64_tr_b16 v[98:99], v142 offset:22592
	v_mfma_f32_32x32x16_bf16 v[34:49], v[174:177], v[90:93], v[34:49]
	v_exp_f32_e32 v202, v50
	v_mfma_f32_32x32x16_bf16 v[34:49], v[178:181], v[94:97], v[34:49]
.Lmla_fast_nostag_e:
	v_exp_f32_e32 v203, v51
	v_exp_f32_e32 v204, v52
	v_exp_f32_e32 v205, v53
	v_exp_f32_e32 v206, v54
	v_exp_f32_e32 v207, v55
	v_exp_f32_e32 v208, v56
	v_exp_f32_e32 v209, v57
	v_exp_f32_e32 v210, v58
	v_exp_f32_e32 v211, v59
	v_exp_f32_e32 v212, v60
	v_exp_f32_e32 v213, v61
	v_exp_f32_e32 v214, v62
	v_exp_f32_e32 v215, v63
	v_exp_f32_e32 v216, v64
	v_exp_f32_e32 v217, v65
	v_cmp_lt_f32_e32 vcc, 0x44800000, v254
	s_cbranch_vccnz .Lmla_fast_rescale_e
.Lmla_fast_ok_e:
	v_cvt_pk_bf16_f32 v166, v202, v203
	v_cvt_pk_bf16_f32 v167, v204, v205
	v_cvt_pk_bf16_f32 v168, v206, v207
	v_cvt_pk_bf16_f32 v169, v208, v209
	s_waitcnt lgkmcnt(0)
	s_nop 0
	v_mfma_f32_32x32x16_bf16 v[18:33], v[126:129], v[166:169], v[18:33]
	s_add_i32 s34, s31, 64
	s_cmp_le_u32 s34, s4
	s_cselect_b32 s42, 1, 0
	s_add_i32 s8, s30, 1
	s_and_b32 s8, s8, 3
	s_mulk_i32 s8, 0x6400
	v_add3_u32 v0, s8, v143, v132
	v_add3_u32 v142, s8, v144, v145
	v_mfma_f32_32x32x16_bf16 v[2:17], v[122:125], v[166:169], v[2:17]
	v_cvt_pk_bf16_f32 v170, v210, v211
	v_cvt_pk_bf16_f32 v171, v212, v213
	v_cvt_pk_bf16_f32 v172, v214, v215
	v_cvt_pk_bf16_f32 v173, v216, v217
	v_exp_f32_e32 v218, v34
	v_exp_f32_e32 v219, v35
	v_mfma_f32_32x32x16_bf16 v[18:33], v[118:121], v[170:173], v[18:33]
	v_exp_f32_e32 v220, v36
	v_exp_f32_e32 v221, v37
	ds_read_b128 v[194:197], v0
	ds_read_b128 v[150:153], v0 offset:32
	v_mfma_f32_32x32x16_bf16 v[2:17], v[114:117], v[170:173], v[2:17]
	v_exp_f32_e32 v222, v38
	v_exp_f32_e32 v223, v39
	v_exp_f32_e32 v224, v40
	v_exp_f32_e32 v225, v41
	v_cvt_pk_bf16_f32 v166, v218, v219
	v_cvt_pk_bf16_f32 v167, v220, v221
	v_cvt_pk_bf16_f32 v168, v222, v223
	v_cvt_pk_bf16_f32 v169, v224, v225
	ds_read_b128 v[158:161], v0 offset:64
	ds_read_b128 v[162:165], v0 offset:96
	v_mfma_f32_32x32x16_bf16 v[18:33], v[110:113], v[166:169], v[18:33]
	v_exp_f32_e32 v226, v42
	v_exp_f32_e32 v227, v43
	v_exp_f32_e32 v228, v44
	v_mfma_f32_32x32x16_bf16 v[2:17], v[106:109], v[166:169], v[2:17]
	v_exp_f32_e32 v229, v45
	v_exp_f32_e32 v230, v46
	v_exp_f32_e32 v231, v47
	v_exp_f32_e32 v232, v48
	v_exp_f32_e32 v233, v49
	ds_read_b128 v[174:177], v0 offset:128
	ds_read_b128 v[178:181], v0 offset:160
	v_cvt_pk_bf16_f32 v170, v226, v227
	v_cvt_pk_bf16_f32 v171, v228, v229
	v_cvt_pk_bf16_f32 v172, v230, v231
	v_cvt_pk_bf16_f32 v173, v232, v233
	s_nop 1
	v_mfma_f32_32x32x16_bf16 v[18:33], v[102:105], v[170:173], v[18:33]
	v_mfma_f32_32x32x16_bf16 v[2:17], v[98:101], v[170:173], v[2:17]
	s_add_i32 s30, s30, 1
	s_add_i32 s31, s31, 64
	v_subrev_u32_e32 v146, 64, v146
	s_cmp_lg_u32 s42, 0
	s_cbranch_scc0 .Lmla_fast_generic
.Lmla_fast_havek_o:
	s_mov_b32 s42, 0
.Lmla_fast_nodma_o:
	s_waitcnt lgkmcnt(0)
	v_mfma_f32_32x32x16_bf16 v[50:65], v[194:197], v[74:77], v[234:249]
	ds_read_b128 v[194:197], v0 offset:6656
	v_add_f32_e32 v254, v202, v203
	v_add_f32_e32 v255, v204, v205
	v_add_f32_e32 v254, v254, v206
	v_add_f32_e32 v255, v255, v207
	v_add_f32_e32 v254, v254, v208
	v_add_f32_e32 v255, v255, v209
	v_mfma_f32_32x32x16_bf16 v[50:65], v[150:153], v[78:81], v[50:65]
	ds_read_b128 v[150:153], v0 offset:6688
	v_add_f32_e32 v254, v254, v210
	v_add_f32_e32 v255, v255, v211
	v_add_f32_e32 v254, v254, v212
	v_add_f32_e32 v255, v255, v213
	v_add_f32_e32 v254, v254, v214
	v_add_f32_e32 v255, v255, v215
	v_mfma_f32_32x32x16_bf16 v[50:65], v[158:161], v[82:85], v[50:65]
	ds_read_b128 v[158:161], v0 offset:6720
	v_add_f32_e32 v254, v254, v216
	v_add_f32_e32 v255, v255, v217
	v_add_f32_e32 v254, v254, v218
	v_add_f32_e32 v255, v255, v219
	v_add_f32_e32 v254, v254, v220
	v_mfma_f32_32x32x16_bf16 v[50:65], v[162:165], v[86:89], v[50:65]
	ds_read_b128 v[162:165], v0 offset:6752
	v_add_f32_e32 v255, v255, v221
	v_add_f32_e32 v254, v254, v222
	v_add_f32_e32 v255, v255, v223
	v_add_f32_e32 v254, v254, v224
	v_add_f32_e32 v255, v255, v225
	v_mfma_f32_32x32x16_bf16 v[50:65], v[174:177], v[90:93], v[50:65]
	ds_read_b128 v[174:177], v0 offset:6784
	v_add_f32_e32 v254, v254, v226
	v_add_f32_e32 v255, v255, v227
	v_add_f32_e32 v254, v254, v228
	v_add_f32_e32 v255, v255, v229
	v_add_f32_e32 v254, v254, v230
	v_mfma_f32_32x32x16_bf16 v[50:65], v[178:181], v[94:97], v[50:65]
	ds_read_b128 v[178:181], v0 offset:6816
	v_add_f32_e32 v255, v255, v231
	v_add_f32_e32 v254, v254, v232
	v_add_f32_e32 v255, v255, v233
	v_add_f32_e32 v254, v254, v255
	v_add_f32_e32 v147, v147, v254
	s_waitcnt lgkmcnt(5)
	v_mfma_f32_32x32x16_bf16 v[34:49], v[194:197], v[74:77], v[234:249]
	ds_read_b64_tr_b16 v[126:127], v142 offset:13312
	ds_read_b64_tr_b16 v[128:129], v142 offset:14848
	ds_read_b64_tr_b16 v[124:125], v142 offset:14912
	ds_read_b64_tr_b16 v[122:123], v142 offset:13376
	s_waitcnt lgkmcnt(8)
	v_mfma_f32_32x32x16_bf16 v[34:49], v[150:153], v[78:81], v[34:49]
	ds_read_b64_tr_b16 v[118:119], v142 offset:16384
	ds_read_b64_tr_b16 v[120:121], v142 offset:17920
	ds_read_b64_tr_b16 v[116:117], v142 offset:17984
	ds_read_b64_tr_b16 v[114:115], v142 offset:16448
	s_waitcnt lgkmcnt(11)
	v_mfma_f32_32x32x16_bf16 v[34:49], v[158:161], v[82:85], v[34:49]
	ds_read_b64_tr_b16 v[110:111], v142 offset:19456
	ds_read_b64_tr_b16 v[112:113], v142 offset:20992
	ds_read_b64_tr_b16 v[108:109], v142 offset:21056
	ds_read_b64_tr_b16 v[106:107], v142 offset:19520
	s_waitcnt lgkmcnt(11)
	v_mfma_f32_32x32x16_bf16 v[34:49], v[162:165], v[86:89], v[34:49]
	ds_read_b64_tr_b16 v[102:103], v142 offset:22528
	ds_read_b64_tr_b16 v[104:105], v142 offset:24064
	ds_read_b64_tr_b16 v[100:101], v142 offset:24128
	ds_read_b64_tr_b16 v[98:99], v142 offset:22592
	v_mfma_f32_32x32x16_bf16 v[34:49], v[174:177], v[90:93], v[34:49]
	v_exp_f32_e32 v202, v50
	v_mfma_f32_32x32x16_bf16 v[34:49], v[178:181], v[94:97], v[34:49]
	s_waitcnt vmcnt(0) lgkmcnt(0)
	s_barrier

.Lmla_fast_ok_o:
	v_cvt_pk_bf16_f32 v166, v202, v203
	v_cvt_pk_bf16_f32 v167, v204, v205
	v_cvt_pk_bf16_f32 v168, v206, v207
	v_cvt_pk_bf16_f32 v169, v208, v209
	s_waitcnt lgkmcnt(0)
	s_nop 0
	v_mfma_f32_32x32x16_bf16 v[18:33], v[126:129], v[166:169], v[18:33]
	s_add_i32 s34, s31, 64
	s_cmp_le_u32 s34, s4
	s_cselect_b32 s42, 1, 0
	s_add_i32 s8, s30, 1
	s_and_b32 s8, s8, 3
	s_mulk_i32 s8, 0x6400
	v_add3_u32 v0, s8, v143, v132
	v_add3_u32 v142, s8, v144, v145
	v_mfma_f32_32x32x16_bf16 v[2:17], v[122:125], v[166:169], v[2:17]
	v_cvt_pk_bf16_f32 v170, v210, v211
	v_cvt_pk_bf16_f32 v171, v212, v213
	v_cvt_pk_bf16_f32 v172, v214, v215
	v_cvt_pk_bf16_f32 v173, v216, v217
	v_exp_f32_e32 v218, v34
	v_exp_f32_e32 v219, v35
	v_mfma_f32_32x32x16_bf16 v[18:33], v[118:121], v[170:173], v[18:33]
	v_exp_f32_e32 v220, v36
	v_exp_f32_e32 v221, v37
	ds_read_b128 v[194:197], v0
	ds_read_b128 v[150:153], v0 offset:32
	v_mfma_f32_32x32x16_bf16 v[2:17], v[114:117], v[170:173], v[2:17]
	v_exp_f32_e32 v222, v38
	v_exp_f32_e32 v223, v39
	v_exp_f32_e32 v224, v40
	v_exp_f32_e32 v225, v41
	v_cvt_pk_bf16_f32 v166, v218, v219
	v_cvt_pk_bf16_f32 v167, v220, v221
	v_cvt_pk_bf16_f32 v168, v222, v223
	v_cvt_pk_bf16_f32 v169, v224, v225
	ds_read_b128 v[158:161], v0 offset:64
	ds_read_b128 v[162:165], v0 offset:96
	v_mfma_f32_32x32x16_bf16 v[18:33], v[110:113], v[166:169], v[18:33]
	v_exp_f32_e32 v226, v42
	v_exp_f32_e32 v227, v43
	v_exp_f32_e32 v228, v44
	v_mfma_f32_32x32x16_bf16 v[2:17], v[106:109], v[166:169], v[2:17]
	v_exp_f32_e32 v229, v45
	v_exp_f32_e32 v230, v46
	v_exp_f32_e32 v231, v47
	v_exp_f32_e32 v232, v48
	v_exp_f32_e32 v233, v49
	ds_read_b128 v[174:177], v0 offset:128
	ds_read_b128 v[178:181], v0 offset:160
	v_cvt_pk_bf16_f32 v170, v226, v227
	v_cvt_pk_bf16_f32 v171, v228, v229
	v_cvt_pk_bf16_f32 v172, v230, v231
	v_cvt_pk_bf16_f32 v173, v232, v233
	s_nop 1
	v_mfma_f32_32x32x16_bf16 v[18:33], v[102:105], v[170:173], v[18:33]
	v_mfma_f32_32x32x16_bf16 v[2:17], v[98:101], v[170:173], v[2:17]
	s_add_i32 s30, s30, 1
	s_add_i32 s31, s31, 64
	v_subrev_u32_e32 v146, 64, v146
	s_cmp_lg_u32 s42, 0
	s_cbranch_scc1 .Lmla_fast_havek_e
	s_branch .Lmla_fast_generic

.Lmla_fast_rescale_e:
	v_frexp_exp_i32_f32_e32 v0, v254
	v_cvt_f32_i32_e32 v0, v0
	v_xor_b32_e32 v149, 32, v187
	v_cmp_lt_i32_e32 vcc, v149, v189
	s_nop 1
	v_cndmask_b32_e32 v149, v187, v149, vcc
	v_lshlrev_b32_e32 v149, 2, v149
	ds_bpermute_b32 v149, v149, v0
	s_waitcnt lgkmcnt(0)
	v_max3_f32 v149, v0, v149, 0
	v_exp_f32_e64 v0, -v149
	v_add_f32_e32 v148, v148, v149
	v_pk_mul_f32 v[32:33], v[32:33], v[0:1] op_sel_hi:[1,0]
	v_pk_mul_f32 v[30:31], v[30:31], v[0:1] op_sel_hi:[1,0]
	v_pk_mul_f32 v[28:29], v[28:29], v[0:1] op_sel_hi:[1,0]
	v_pk_mul_f32 v[26:27], v[26:27], v[0:1] op_sel_hi:[1,0]
	v_pk_mul_f32 v[24:25], v[24:25], v[0:1] op_sel_hi:[1,0]
	v_pk_mul_f32 v[22:23], v[22:23], v[0:1] op_sel_hi:[1,0]
	v_pk_mul_f32 v[20:21], v[20:21], v[0:1] op_sel_hi:[1,0]
	v_pk_mul_f32 v[18:19], v[18:19], v[0:1] op_sel_hi:[1,0]
	v_pk_mul_f32 v[16:17], v[16:17], v[0:1] op_sel_hi:[1,0]
	v_pk_mul_f32 v[14:15], v[14:15], v[0:1] op_sel_hi:[1,0]
	v_pk_mul_f32 v[12:13], v[12:13], v[0:1] op_sel_hi:[1,0]
	v_pk_mul_f32 v[10:11], v[10:11], v[0:1] op_sel_hi:[1,0]
	v_pk_mul_f32 v[8:9], v[8:9], v[0:1] op_sel_hi:[1,0]
	v_pk_mul_f32 v[6:7], v[6:7], v[0:1] op_sel_hi:[1,0]
	v_pk_mul_f32 v[4:5], v[4:5], v[0:1] op_sel_hi:[1,0]
	v_pk_mul_f32 v[2:3], v[2:3], v[0:1] op_sel_hi:[1,0]
	v_mul_f32_e32 v147, v147, v0
	v_sub_f32_e32 v234, v234, v149
	v_sub_f32_e32 v235, v235, v149
	v_sub_f32_e32 v236, v236, v149
	v_sub_f32_e32 v237, v237, v149
	v_sub_f32_e32 v238, v238, v149
	v_sub_f32_e32 v239, v239, v149
	v_sub_f32_e32 v240, v240, v149
	v_sub_f32_e32 v241, v241, v149
	v_sub_f32_e32 v242, v242, v149
	v_sub_f32_e32 v243, v243, v149
	v_sub_f32_e32 v244, v244, v149
	v_sub_f32_e32 v245, v245, v149
	v_sub_f32_e32 v246, v246, v149
	v_sub_f32_e32 v247, v247, v149
	v_sub_f32_e32 v248, v248, v149
	v_sub_f32_e32 v249, v249, v149
	v_sub_f32_e32 v50, v50, v149
	v_sub_f32_e32 v51, v51, v149
	v_sub_f32_e32 v52, v52, v149
	v_sub_f32_e32 v53, v53, v149
	v_sub_f32_e32 v54, v54, v149
	v_sub_f32_e32 v55, v55, v149
	v_sub_f32_e32 v56, v56, v149
	v_sub_f32_e32 v57, v57, v149
	v_sub_f32_e32 v58, v58, v149
	v_sub_f32_e32 v59, v59, v149
	v_sub_f32_e32 v60, v60, v149
	v_sub_f32_e32 v61, v61, v149
	v_sub_f32_e32 v62, v62, v149
	v_sub_f32_e32 v63, v63, v149
	v_sub_f32_e32 v64, v64, v149
	v_sub_f32_e32 v65, v65, v149
	v_sub_f32_e32 v34, v34, v149
	v_sub_f32_e32 v35, v35, v149
	v_sub_f32_e32 v36, v36, v149
	v_sub_f32_e32 v37, v37, v149
	v_sub_f32_e32 v38, v38, v149
	v_sub_f32_e32 v39, v39, v149
	v_sub_f32_e32 v40, v40, v149
	v_sub_f32_e32 v41, v41, v149
	v_sub_f32_e32 v42, v42, v149
	v_sub_f32_e32 v43, v43, v149
	v_sub_f32_e32 v44, v44, v149
	v_sub_f32_e32 v45, v45, v149
	v_sub_f32_e32 v46, v46, v149
	v_sub_f32_e32 v47, v47, v149
	v_sub_f32_e32 v48, v48, v149
	v_sub_f32_e32 v49, v49, v149
	v_exp_f32_e32 v202, v50
	v_exp_f32_e32 v203, v51
	v_exp_f32_e32 v204, v52
	v_exp_f32_e32 v205, v53
	v_exp_f32_e32 v206, v54
	v_exp_f32_e32 v207, v55
	v_exp_f32_e32 v208, v56
	v_exp_f32_e32 v209, v57
	v_exp_f32_e32 v210, v58
	v_exp_f32_e32 v211, v59
	v_exp_f32_e32 v212, v60
	v_exp_f32_e32 v213, v61
	v_exp_f32_e32 v214, v62
	v_exp_f32_e32 v215, v63
	v_exp_f32_e32 v216, v64
	v_exp_f32_e32 v217, v65
	s_branch .Lmla_fast_ok_e
.Lmla_fast_rescale_o:
	v_frexp_exp_i32_f32_e32 v0, v254
	v_cvt_f32_i32_e32 v0, v0
	v_xor_b32_e32 v149, 32, v187
	v_cmp_lt_i32_e32 vcc, v149, v189
	s_nop 1
	v_cndmask_b32_e32 v149, v187, v149, vcc
	v_lshlrev_b32_e32 v149, 2, v149
	ds_bpermute_b32 v149, v149, v0
	s_waitcnt lgkmcnt(0)
	v_max3_f32 v149, v0, v149, 0
	v_exp_f32_e64 v0, -v149
	v_add_f32_e32 v148, v148, v149
	v_pk_mul_f32 v[32:33], v[32:33], v[0:1] op_sel_hi:[1,0]
	v_pk_mul_f32 v[30:31], v[30:31], v[0:1] op_sel_hi:[1,0]
	v_pk_mul_f32 v[28:29], v[28:29], v[0:1] op_sel_hi:[1,0]
	v_pk_mul_f32 v[26:27], v[26:27], v[0:1] op_sel_hi:[1,0]
	v_pk_mul_f32 v[24:25], v[24:25], v[0:1] op_sel_hi:[1,0]
	v_pk_mul_f32 v[22:23], v[22:23], v[0:1] op_sel_hi:[1,0]
	v_pk_mul_f32 v[20:21], v[20:21], v[0:1] op_sel_hi:[1,0]
	v_pk_mul_f32 v[18:19], v[18:19], v[0:1] op_sel_hi:[1,0]
	v_pk_mul_f32 v[16:17], v[16:17], v[0:1] op_sel_hi:[1,0]
	v_pk_mul_f32 v[14:15], v[14:15], v[0:1] op_sel_hi:[1,0]
	v_pk_mul_f32 v[12:13], v[12:13], v[0:1] op_sel_hi:[1,0]
	v_pk_mul_f32 v[10:11], v[10:11], v[0:1] op_sel_hi:[1,0]
	v_pk_mul_f32 v[8:9], v[8:9], v[0:1] op_sel_hi:[1,0]
	v_pk_mul_f32 v[6:7], v[6:7], v[0:1] op_sel_hi:[1,0]
	v_pk_mul_f32 v[4:5], v[4:5], v[0:1] op_sel_hi:[1,0]
	v_pk_mul_f32 v[2:3], v[2:3], v[0:1] op_sel_hi:[1,0]
	v_mul_f32_e32 v147, v147, v0
	v_sub_f32_e32 v234, v234, v149
	v_sub_f32_e32 v235, v235, v149
	v_sub_f32_e32 v236, v236, v149
	v_sub_f32_e32 v237, v237, v149
	v_sub_f32_e32 v238, v238, v149
	v_sub_f32_e32 v239, v239, v149
	v_sub_f32_e32 v240, v240, v149
	v_sub_f32_e32 v241, v241, v149
	v_sub_f32_e32 v242, v242, v149
	v_sub_f32_e32 v243, v243, v149
	v_sub_f32_e32 v244, v244, v149
	v_sub_f32_e32 v245, v245, v149
	v_sub_f32_e32 v246, v246, v149
	v_sub_f32_e32 v247, v247, v149
	v_sub_f32_e32 v248, v248, v149
	v_sub_f32_e32 v249, v249, v149
	v_sub_f32_e32 v50, v50, v149
	v_sub_f32_e32 v51, v51, v149
	v_sub_f32_e32 v52, v52, v149
	v_sub_f32_e32 v53, v53, v149
	v_sub_f32_e32 v54, v54, v149
	v_sub_f32_e32 v55, v55, v149
	v_sub_f32_e32 v56, v56, v149
	v_sub_f32_e32 v57, v57, v149
	v_sub_f32_e32 v58, v58, v149
	v_sub_f32_e32 v59, v59, v149
	v_sub_f32_e32 v60, v60, v149
	v_sub_f32_e32 v61, v61, v149
	v_sub_f32_e32 v62, v62, v149
	v_sub_f32_e32 v63, v63, v149
	v_sub_f32_e32 v64, v64, v149
	v_sub_f32_e32 v65, v65, v149
	v_sub_f32_e32 v34, v34, v149
	v_sub_f32_e32 v35, v35, v149
	v_sub_f32_e32 v36, v36, v149
	v_sub_f32_e32 v37, v37, v149
	v_sub_f32_e32 v38, v38, v149
	v_sub_f32_e32 v39, v39, v149
	v_sub_f32_e32 v40, v40, v149
	v_sub_f32_e32 v41, v41, v149
	v_sub_f32_e32 v42, v42, v149
	v_sub_f32_e32 v43, v43, v149
	v_sub_f32_e32 v44, v44, v149
	v_sub_f32_e32 v45, v45, v149
	v_sub_f32_e32 v46, v46, v149
	v_sub_f32_e32 v47, v47, v149
	v_sub_f32_e32 v48, v48, v149
	v_sub_f32_e32 v49, v49, v149
	v_exp_f32_e32 v202, v50
	v_exp_f32_e32 v203, v51
	v_exp_f32_e32 v204, v52
	v_exp_f32_e32 v205, v53
	v_exp_f32_e32 v206, v54
	v_exp_f32_e32 v207, v55
	v_exp_f32_e32 v208, v56
	v_exp_f32_e32 v209, v57
	v_exp_f32_e32 v210, v58
	v_exp_f32_e32 v211, v59
	v_exp_f32_e32 v212, v60
	v_exp_f32_e32 v213, v61
	v_exp_f32_e32 v214, v62
	v_exp_f32_e32 v215, v63
	v_exp_f32_e32 v216, v64
	v_exp_f32_e32 v217, v65
	s_branch .Lmla_fast_ok_o
